# equal wave priority during the scan/mLSTM phases P2-P4, static priority for waves 0-3 restored at the GLU GEMM
# baseline (speedup 1.0000x reference)
; __device__ __forceinline__ void mlstm_local(const Params& P, unsigned char* shm, int bh, int j) {
;     const int tid = threadIdx.x, lane = tid & 63, wave = tid >> 6, l16 = lane & 15, q = lane >> 4;
;     const int b = bh >> 2, h = bh & 3;
;     bf16_t* Kt = (bf16_t*)shm; bf16_t* Vt = (bf16_t*)(shm + 69632); float* sm = (float*)(shm + SM_OFF);
;     const float* gif = (const float*)(P.ws + O_GIF); const bf16_t* PROJ = (const bf16_t*)(P.ws + O_PROJ);
;     gate_chain(gif, b, h, j, sm);
;     const float m_in = sm[320]; const float Ml = fmaxf(m_in, sm[288 + j]);
;     if (tid == 0) { float* gst = (float*)(P.ws + O_GST); gst[(bh * 17 + j) * 2] = sm[256 + j]; gst[(bh * 17 + j) * 2 + 1] = sm[288 + j]; }
;     const int L = j == 0 ? 16 : 128; const int rowb = j == 0 ? ROW_META : b * 2048 + (j - 1) * 128;
;     const int niter = j == 0 ? 2 : 8;
; #pragma unroll 2
;     for (int i = 0; i < niter; ++i) { const int item = tid + 512 * i; const int s = ((item >> 9) << 4) | (item & 15), c8 = (item >> 4) & 31;
;         u32x4 kw = (u32x4){0u, 0u, 0u, 0u}, vw = (u32x4){0u, 0u, 0u, 0u}; float w = 0.f;
;         if (s < L) { const bf16_t* rp = PROJ + (size_t)(rowb + s) * NPROJ + h * 256 + c8 * 8; kw = *(const u32x4*)(rp + C_K); vw = *(const u32x4*)(rp + C_V); w = __expf(sm[s] - Ml) * 0.0625f; }
;         f32x4 k0, k1; unpack8(kw, k0, k1);
;         bf16_t* kd = Kt + (size_t)(c8 * 8) * 136 + s; bf16_t* vd = Vt + (size_t)(c8 * 8) * 136 + s;
;         kd[0 * 136] = f2bf(k0[0] * w); kd[1 * 136] = f2bf(k0[1] * w); kd[2 * 136] = f2bf(k0[2] * w); kd[3 * 136] = f2bf(k0[3] * w);
; __global__ void __launch_bounds__(512, 2) fwd(Params P) {
;     ...
;     if (IN(2)) for (int rep_ = 0; rep_ < NREP(2); ++rep_) {
;         for (int r2 = 0; r2 < NREP(14); ++r2) for (int u = blockIdx.x; u < 272; u += gridDim.x) { if (u < 256) mlstm_local(P, shm, u >> 4, (u & 15) + 1); else mlstm_local(P, shm, u - 256, 0); }
;         __syncthreads();
;         for (int r2 = 0; r2 < NREP(15); ++r2) for (int id = blockIdx.x * 8 + wave; id < 4672; id += gridDim.x * 8) {
;             if (id < 2048 && (id & 7) == 0) { mlstm_decode_wave(P, shm + wave * S5_WL, id >> 3); continue; }
;             const int sidx = id < 2048 ? id - (id >> 3) - 1 : 1792 + (id - 2048);
;             if (sidx < 3904) s5_unit<0>(P, shm + wave * S5_WL, sidx); else s5_unit<2>(P, shm + wave * S5_WL, sidx - 3904); }
.LBB0_289:
	s_cmp_lt_i32 s14, 3
	s_cselect_b64 s[0:1], -1, 0
	s_cmp_gt_i32 s15, 2
	s_cselect_b64 s[2:3], -1, 0
	s_and_b64 s[0:1], s[0:1], s[2:3]
	s_andn2_b64 vcc, exec, s[0:1]
	s_cbranch_vccnz .LBB0_430
	s_setprio 0
	s_add_u32 s0, s12, 0x4542000
	v_writelane_b32 v245, s93, 52
	s_addc_u32 s1, s13, 0
	v_writelane_b32 v245, s0, 54
	v_and_b32_e32 v147, 15, v214
	v_and_b32_e32 v146, 63, v214
	v_writelane_b32 v245, s1, 55
	s_add_u32 s0, s12, 0x4500000
	s_addc_u32 s1, s13, 0
	v_writelane_b32 v245, s0, 56
	s_cmpk_gt_i32 s94, 0x10f
	v_mov_b32_e32 v67, 0
	s_mov_b32 s85, 0
	v_cmp_eq_u32_e64 s[2:3], 0, v146
	v_cmp_gt_u32_e64 s[4:5], 32, v146
	v_lshlrev_b32_e32 v64, 2, v147
	v_lshlrev_b32_e32 v148, 1, v147
	v_writelane_b32 v245, s1, 57
	s_cbranch_scc1 .LBB0_343
	v_lshlrev_b32_e32 v66, 6, v214
	v_bfe_u32 v0, v214, 4, 5
	v_lshl_add_u64 v[68:69], s[12:13], 0, v[66:67]
	v_mul_u32_u24_e32 v1, 0x440, v0
	v_lshlrev_b32_e32 v66, 4, v0
	v_bfe_u32 v4, v214, 4, 2
	s_add_i32 s7, 0, 0x22000
	v_lshlrev_b32_e32 v8, 1, v1
	v_lshl_add_u64 v[0:1], s[12:13], 0, v[66:67]
	v_mul_u32_u24_e32 v2, 0x4800, v147
	v_mov_b32_e32 v3, v67
	s_add_u32 s68, s12, 0x1e5ca000
	v_lshl_add_u64 v[70:71], v[0:1], 0, v[2:3]
	v_lshl_or_b32 v0, v215, 5, v147
	v_lshlrev_b32_e32 v1, 4, v4
	s_movk_i32 s91, 0x110
	v_mov_b32_e32 v65, v67
	v_lshlrev_b32_e32 v2, 15, v215
	s_addc_u32 s79, s13, 0
	s_add_i32 s0, 0, 0x11000
	v_mad_u32_u24 v11, v0, s91, v1
	v_add_u32_e32 v80, 0, v1
	v_lshl_add_u64 v[0:1], s[12:13], 0, v[64:65]
	v_lshl_or_b32 v2, v4, 12, v2
	v_add_u32_e32 v10, s0, v8
	v_add_u32_e32 v77, s0, v11
	v_lshl_add_u64 v[0:1], v[0:1], 0, v[2:3]
	s_mov_b64 s[0:1], 0x1a142000
	v_lshl_add_u64 v[72:73], v[0:1], 0, s[0:1]
	v_lshrrev_b32_e32 v0, 5, v214
	v_and_or_b32 v0, v0, 16, v147
	v_add_u32_e32 v9, 0, v8
	v_lshl_add_u32 v83, v0, 2, s7
	v_lshlrev_b32_e32 v0, 1, v0
	v_add_u32_e32 v86, 0x200, v214
	v_add_u32_e32 v84, v9, v0
	v_add_u32_e32 v85, v10, v0
	v_lshrrev_b32_e32 v0, 5, v86
	v_and_or_b32 v0, v0, 48, v147
	v_lshlrev_b32_e32 v0, 1, v0
	v_lshlrev_b32_e32 v6, 2, v215
	v_add_u32_e32 v87, v9, v0
	v_add_u32_e32 v88, v10, v0
	v_mov_b32_e32 v0, 0xffffff80
	v_lshl_add_u32 v89, v215, 7, v0
	v_add_u32_e32 v0, 0, v6
	v_add_u32_e32 v90, 0x22480, v0
	v_lshrrev_b32_e32 v0, 9, v86
	v_lshlrev_b32_e32 v1, 5, v0
	s_mov_b32 s6, 0x22000
	v_or3_b32 v91, v1, v8, v148
	v_lshlrev_b32_e32 v1, 6, v0
	v_lshl_or_b32 v93, v0, 4, v147
	v_lshrrev_b32_e32 v0, 9, v214
	v_lshlrev_b32_e32 v5, 3, v214
	s_movk_i32 s0, 0x100
	v_or3_b32 v92, v1, v64, s6
	v_lshl_or_b32 v94, v0, 4, v147
	v_lshlrev_b32_e32 v1, 6, v0
	v_lshlrev_b32_e32 v0, 5, v0
	v_cmp_gt_u32_e64 s[18:19], s0, v214
	v_readlane_b32 s0, v245, 54
	v_or3_b32 v96, v0, v8, v148
	v_add_u32_e32 v0, 0, v5
	v_readlane_b32 s1, v245, 55
	v_add_u32_e32 v98, 0x22000, v0
	v_mbcnt_lo_u32_b32 v0, -1, 0
	v_add_u32_e32 v7, s7, v6
	s_add_u32 s86, s12, 0x1e542000
	v_lshl_add_u64 v[74:75], s[0:1], 0, v[66:67]
	s_movk_i32 s0, 0x200
	v_mbcnt_hi_u32_b32 v102, -1, v0
	v_bfrev_b32_e32 v0, 0.5
	v_cmp_gt_u32_e64 s[56:57], 64, v214
	v_cmp_gt_u32_e64 s[58:59], 2, v214
	v_cmp_gt_u32_e64 s[60:61], 4, v214
	v_cmp_gt_u32_e64 s[62:63], 8, v214
	v_cmp_gt_u32_e64 s[64:65], 16, v214
	v_cmp_gt_u32_e64 s[66:67], 32, v214
	s_movk_i32 s89, 0x4800
	v_mul_u32_u24_e32 v65, 0x110, v214
	s_addc_u32 s87, s13, 0
	v_lshlrev_b32_e32 v81, 1, v146
	v_cmp_gt_u32_e64 s[20:21], 2, v146
	v_cmp_gt_u32_e64 s[22:23], 4, v146
	v_cmp_gt_u32_e64 s[24:25], 8, v146
	v_cmp_gt_u32_e64 s[26:27], 16, v146
	v_lshl_add_u32 v82, v146, 3, s7
	v_cmp_gt_u32_e64 s[28:29], s0, v214
	s_add_i32 s50, s94, 1
	v_or3_b32 v95, v1, v64, s6
	v_add_u32_e32 v97, 0, v11
	s_mov_b32 s51, 0xbfb8aa3b
	s_mov_b32 s6, 0x3f2aaaab
	s_mov_b32 s88, 0x3e9b6dac
	s_mov_b32 s90, 0x3f2aaada
	s_mov_b32 s92, 0x3f317218
	s_mov_b32 s8, 0xb102e308
	s_mov_b32 s7, 0x7f800000
	s_mov_b32 s30, 0x33800000
	s_add_i32 s31, 0, 0x22500
	s_add_i32 s82, 0, 0x22400
	s_movk_i32 s9, 0x7fff
	s_movk_i32 s33, 0x4000
	v_mov_b32_e32 v76, 0x3ecc95a3
	v_mov_b32_e32 v99, 0x7f800000
	v_mov_b32_e32 v100, 0x7fc00000
	v_mov_b32_e32 v101, 0xff800000
	v_lshl_or_b32 v103, v102, 2, v0
	v_add_u32_e32 v104, 0x400, v7
	v_mov_b32_e32 v105, 0x80
	v_mov_b32_e32 v106, 0x2080
	s_mov_b32 s93, s94
	s_mov_b32 s69, 0
	s_mov_b32 s70, s94
	s_branch .LBB0_294

;     __device__ bool next(int i, Unit& u) const {
;         long L = (long)i * G + c; if (L >= (long)nwg * rep) return false;
;         L %= nwg;
;         int wgid = (int)L; { const int q = nwg / NXCD, r = nwg % NXCD, xcd = wgid % NXCD, off = wgid / NXCD; wgid = (xcd < r ? xcd * (q + 1) : r * (q + 1) + (xcd - r) * q) + off; }
;         const int nig = WGM * nN, gid = wgid / nig, fm = gid * WGM, gsz = (nM - fm) < WGM ? (nM - fm) : WGM;
;         u.pm = fm + ((wgid % nig) % gsz); u.pn = (wgid % nig) / gsz; return true;
;     }
; template <class Epi>
; __device__ __forceinline__ void gemm_phase(LAS unsigned char* lds, const Gemm g, const StaticOrder& S, const Epi& E) {
;     const int tid = threadIdx.x, wid = __builtin_amdgcn_readfirstlane(tid >> 6), lane = tid & 63, wr = wid >> 2, wc = wid & 3, fr = lane & 15, fq = lane >> 4;
;     const int K = g.K, nt = K / BK;
;     unsigned voffA[2], voffB[2];
; #pragma unroll
;     for (int i = 0; i < 2; ++i) { int R, C; stage_rc(tid * 16 + i * 8192, R, C); const int Rb = Epi::PERM ? ((R & ~31) + perm32(R & 31)) : R;
;         voffA[i] = (unsigned)(R * K + C) * 2u; voffB[i] = (unsigned)(Rb * K + C) * 2u; }
;     const size_t kstep = (size_t)(BK * 2);
;     const size_t hstep = (size_t)HALF * K * 2;
;     const size_t tstep = 2 * hstep;
;     const unsigned ldsw = (unsigned)wid * 1024u;
;     const int aoff = lds_byte(wr * 64 + fr, fq * 8), boff = lds_byte(wc * 32 + fr, fq * 8);
;     ...
;     Unit cur, nxt; int ui = 0;
;     if (!S.next(0, cur)) return;
;     f32x4 acc[2][2][4][2];
; #pragma unroll
;     for (int a = 0; a < 2; ++a)
; #pragma unroll
;         for (int b = 0; b < 2; ++b)
; #pragma unroll
;             for (int m = 0; m < 4; ++m)
; #pragma unroll
;                 for (int n = 0; n < 2; ++n) acc[a][b][m][n] = (f32x4){0.f, 0.f, 0.f, 0.f};
;     bf16x8 At[4][2], B0[2][2], B1[2][2];
;     const char* cA = (const char*)g.A + (size_t)cur.pm * tstep; const char* cB = (const char*)g.Bt + (size_t)cur.pn * tstep;
; __global__ void __launch_bounds__(512, 2) fwd(Params P) {
;     ...
;     if (IN(5)) for (int rep_ = 0; rep_ < NREP(5); ++rep_) { pg8::Gemm g{(const bf16_t*)(ws + O_G), (const bf16_t*)(ws + O_WGLUT), MP, 1024, 1024}; pg8::StaticOrder S; S.init(MP, 1024, gridDim.x, blockIdx.x);
;         EpiGlu E{(const bf16_t*)(ws + O_G), (bf16_t*)(ws + O_YA), P.in[19]}; pg8::gemm_phase<EpiGlu>((LAS unsigned char*)shm, g, S, E);
.LBB0_727:
	s_cmp_lt_i32 s14, 6
	s_cselect_b64 s[0:1], -1, 0
	s_cmp_gt_i32 s15, 5
	s_cselect_b64 s[2:3], -1, 0
	s_and_b64 s[0:1], s[0:1], s[2:3]
	s_andn2_b64 vcc, exec, s[0:1]
	s_cbranch_vccnz .LBB0_902
	v_readfirstlane_b32 s0, v214
	s_nop 3
	s_cmpk_ge_u32 s0, 0x100
	s_cbranch_scc1 .Lprio5_done
	s_setprio 1
.Lprio5_done:
	s_add_u32 s6, s12, 0x2100000
	s_addc_u32 s7, s13, 0
	s_add_u32 s8, s12, 0xd9c2000
	s_addc_u32 s9, s13, 0
	v_lshrrev_b32_e32 v192, 3, v214
	v_and_b32_e32 v194, 15, v214
	s_cmpk_gt_i32 s94, 0x83
	v_lshrrev_b32_e32 v193, 4, v214
	s_movk_i32 s0, 0x60
	v_readfirstlane_b32 s33, v214
	s_cbranch_scc1 .LBB0_744
	v_lshrrev_b32_e32 v2, 1, v214
	v_and_b32_e32 v11, 24, v2
	v_lshrrev_b32_e32 v2, 5, v214
	v_lshlrev_b32_e32 v0, 4, v214
	v_and_b32_e32 v1, 32, v214
	v_and_b32_e32 v2, 4, v2
	v_bfe_u32 v3, v214, 2, 2
	v_bfe_u32 v10, v214, 2, 4
	v_bitop3_b32 v8, v0, v1, 48 bitop3:0x6c
	v_and_b32_e32 v9, 64, v214
	v_or3_b32 v2, v2, v3, v11
	s_movk_i32 s1, 0x70
	v_add_u32_e32 v12, 0x2000, v0
	v_or_b32_e32 v1, v8, v9
	v_and_or_b32 v3, v192, s1, v10
	v_and_or_b32 v4, v192, s0, v2
	v_lshrrev_b32_e32 v0, 7, v12
	s_movk_i32 s0, 0xf0
	v_lshl_or_b32 v164, v3, 11, v1
	v_and_or_b32 v3, v0, s0, v10
	s_movk_i32 s0, 0xe0
	v_and_or_b32 v0, v0, s0, v2
	s_mul_hi_i32 s0, s94, 0x3e0f83e1
	s_lshr_b32 s1, s0, 31
	s_lshr_b32 s0, s0, 5
	s_add_i32 s0, s0, s1
	s_mulk_i32 s0, 0x84
	s_sub_i32 s0, s94, s0
	s_sext_i32_i16 s1, s0
	s_bfe_u32 s1, s1, 0x3001c
	s_add_i32 s1, s0, s1
	s_sext_i32_i16 s2, s1
	s_and_b32 s1, s1, 0xfff8
	s_sub_i32 s0, s0, s1
	s_lshr_b32 s10, s33, 6
	s_lshl_b32 s4, s0, 4
	s_lshr_b32 s3, s33, 8
	s_lshl_b32 s44, s10, 10
	s_ashr_i32 s2, s2, 3
	s_mul_i32 s1, s0, 17
	s_or_b32 s4, s4, 4
	s_sext_i32_i16 s0, s0
	s_cmp_lt_i32 s0, 4
	s_cselect_b32 s0, s1, s4
	s_add_i32 s0, s0, s2
	s_sext_i32_i16 s1, s0
	s_bfe_u32 s1, s1, 0x5001a
	s_add_i32 s1, s0, s1
	s_sext_i32_i16 s2, s1
	s_ashr_i32 s2, s2, 5
	s_lshl_b32 s4, s2, 3
	s_sub_i32 s2, 33, s4
	s_and_b32 s1, s1, 0xffe0
	s_min_u32 s5, s2, 8
	s_sub_i32 s11, s0, s1
	v_lshl_or_b32 v168, v3, 11, v1
	s_sext_i32_i16 s0, s11
	v_cvt_f32_ubyte0_e32 v3, s5
	v_lshl_or_b32 v166, v4, 11, v1
	v_cvt_f32_i32_e32 v2, s0
	v_rcp_iflag_f32_e32 v4, v3
	v_lshl_or_b32 v170, v0, 11, v1
	s_ashr_i32 s0, s0, 30
	s_or_b32 s2, s0, 1
	v_mul_f32_e32 v0, v2, v4
	v_trunc_f32_e32 v0, v0
	v_fma_f32 v1, -v0, v3, v2
	v_cvt_i32_f32_e32 v0, v0
	v_cmp_ge_f32_e64 s[0:1], |v1|, v3
	s_and_b64 s[0:1], s[0:1], exec
	s_cselect_b32 s0, s2, 0
	v_readfirstlane_b32 s1, v0
	s_add_i32 s2, s1, s0
	s_mul_i32 s0, s2, s5
	s_sub_i32 s0, s11, s0
	s_sext_i32_i8 s0, s0
	s_add_i32 s30, s4, s0
	s_ashr_i32 s31, s30, 31
	s_bfe_i64 s[4:5], s[2:3], 0x80000
	s_lshl_b64 s[0:1], s[30:31], 19
	s_lshl_b64 s[4:5], s[4:5], 19
	s_add_u32 s40, s8, s4
	s_addc_u32 s41, s9, s5
	s_add_i32 s31, s44, 0
	s_add_i32 m0, s31, 0x10000
	v_mov_b32_e32 v167, 0
	global_load_lds_dwordx4 v166, s[40:41]
	s_add_i32 m0, s31, 0x12000
	s_add_u32 s34, s6, s0
	global_load_lds_dwordx4 v170, s[40:41]
	s_addc_u32 s35, s7, s1
	s_mov_b32 m0, s31
	s_add_i32 s45, s31, 0x2000
	global_load_lds_dwordx4 v164, s[34:35]
	s_mov_b32 m0, s45
	s_add_u32 s0, s40, 0x40000
	global_load_lds_dwordx4 v168, s[34:35]
	s_addc_u32 s1, s41, 0
	s_add_i32 m0, s31, 0x14000
	v_mov_b32_e32 v171, v167
	global_load_lds_dwordx4 v166, s[0:1]
	s_add_i32 m0, s31, 0x16000
	v_mov_b32_e32 v165, v167
	global_load_lds_dwordx4 v170, s[0:1]
	s_add_u32 s0, s34, 0x40000
	s_addc_u32 s1, s35, 0
	s_add_i32 s46, s31, 0x4000
	s_mov_b32 m0, s46
	s_add_i32 s47, s31, 0x6000
	global_load_lds_dwordx4 v164, s[0:1]
	s_mov_b32 m0, s47
	v_mov_b32_e32 v169, v167
	global_load_lds_dwordx4 v168, s[0:1]
	s_mov_b32 s48, 0
	v_lshl_add_u64 v[6:7], s[40:41], 0, v[166:167]
	v_lshl_add_u64 v[4:5], s[40:41], 0, v[170:171]
	v_lshl_add_u64 v[2:3], s[34:35], 0, v[164:165]
	v_lshl_add_u64 v[0:1], s[34:35], 0, v[168:169]
	s_cmp_lg_u32 s3, 1
	s_mov_b64 s[0:1], 0x40000
	s_cbranch_scc1 .LBB0_731
	s_barrier
